# two back-to-back workgroup barriers dropped (G3 closing barrier before the cross-attention stage's opening barrier; second barrier of the stick-breaking queue pop), on the stacked version
# speedup vs baseline: 1.0007x; 1.0007x over previous
.LBB0_454:
	s_or_b64 exec, exec, s[10:11]
	v_mov_b32_e32 v0, s80
	s_waitcnt lgkmcnt(0)
	s_barrier
	ds_read_b32 v0, v0
	s_movk_i32 s10, 0x1ff
	s_waitcnt lgkmcnt(0)
	v_cmp_lt_i32_e32 vcc, s10, v0
	v_readfirstlane_b32 s12, v0
	s_mov_b64 s[10:11], -1
	s_cbranch_vccnz .LBB0_449
	v_mov_b32_e32 v34, v232
	s_and_b32 s51, s12, 7
	v_readfirstlane_b32 s10, v34
	s_ashr_i32 s13, s10, 6
	s_lshl_b32 s10, s12, 8
	s_and_b32 s72, s10, 0x3800
	s_lshl_b32 s10, s12, 2
	s_and_b32 s10, s10, 0xffffff00
	s_lshl_b32 s11, s13, 5
	s_sub_i32 s85, s11, s10
	v_and_b32_e32 v92, 31, v34
	s_addk_i32 s85, 0x700
	v_or_b32_e32 v82, s85, v92
	s_mov_b32 s73, s77
	v_ashrrev_i32_e32 v83, 31, v82
	s_lshl_b32 s14, s51, 6
	v_lshl_add_u64 v[2:3], v[82:83], 0, s[72:73]
	v_mov_b64_e32 v[4:5], s[68:69]
	s_or_b32 s15, s14, 0x800
	v_mad_u64_u32 v[6:7], s[10:11], v2, s83, v[4:5]
	v_bfe_u32 v35, v34, 5, 1
	v_mad_i32_i24 v7, v3, s83, v7
	s_lshl_b32 s58, s15, 1
	s_mov_b32 s59, s77
	v_lshl_add_u64 v[2:3], v[6:7], 0, s[58:59]
	v_lshlrev_b32_e32 v0, 4, v35
	v_lshl_add_u64 v[2:3], v[2:3], 0, v[0:1]
	global_load_dwordx4 v[50:53], v[2:3], off
	global_load_dwordx4 v[54:57], v[2:3], off offset:32
	global_load_dwordx4 v[58:61], v[2:3], off offset:64
	global_load_dwordx4 v[62:65], v[2:3], off offset:96
	s_lshl_b32 s73, s13, 14
	s_or_b32 s16, s14, 0xa00
	s_or_b32 s12, s14, 0xc00
	s_add_i32 s73, s73, 0
	s_ashr_i32 s10, s85, 31
	v_lshrrev_b32_e32 v0, 1, v34
	v_bfe_u32 v83, v34, 3, 3
	s_add_u32 s55, s85, s72
	v_xor_b32_e32 v0, v0, v34
	v_and_b32_e32 v2, 3, v34
	v_and_or_b32 v36, v0, 4, v2
	v_or_b32_e32 v0, s55, v83
	s_addc_u32 s59, s10, 0
	v_mad_u64_u32 v[8:9], s[10:11], v0, s83, v[4:5]
	v_bitop3_b32 v37, v83, v34, 7 bitop3:0x78
	v_mad_i32_i24 v9, s59, v240, v9
	s_lshl_b32 s76, s16, 1
	v_lshl_add_u64 v[2:3], v[8:9], 0, s[76:77]
	v_lshlrev_b32_e32 v0, 4, v37
	v_lshl_add_u64 v[2:3], v[2:3], 0, v[0:1]
	v_or_b32_e32 v93, 8, v83
	v_or_b32_e32 v94, 16, v83
	v_or_b32_e32 v95, 24, v83
	s_lshl_b32 s74, s12, 1
	s_mov_b32 s75, s77
	v_lshl_add_u64 v[8:9], v[8:9], 0, s[74:75]
	s_ashr_i32 s12, s85, 5
	v_lshlrev_b32_e32 v97, 2, v35
	s_barrier
	s_mov_b32 s10, m0
	s_mov_b32 m0, s73
	s_nop 0
	global_load_lds_dwordx4 v[2:3], off
	s_mov_b32 m0, s10
	v_or_b32_e32 v2, s55, v93
	v_mad_u64_u32 v[6:7], s[10:11], v2, s83, v[4:5]
	v_mad_i32_i24 v7, s59, v240, v7
	v_lshl_add_u64 v[2:3], v[6:7], 0, s[76:77]
	v_lshl_add_u64 v[2:3], v[2:3], 0, v[0:1]
	s_add_i32 s10, s73, 0x400
	s_mov_b32 s11, m0
	s_mov_b32 m0, s10
	s_nop 0
	global_load_lds_dwordx4 v[2:3], off
	s_mov_b32 m0, s11
	v_or_b32_e32 v2, s55, v94
	v_mad_u64_u32 v[2:3], s[10:11], v2, s83, v[4:5]
	v_mad_i32_i24 v3, s59, v240, v3
	v_lshl_add_u64 v[10:11], v[2:3], 0, s[76:77]
	v_lshl_add_u64 v[10:11], v[10:11], 0, v[0:1]
	s_add_i32 s10, s73, 0x800
	s_mov_b32 s11, m0
	s_mov_b32 m0, s10
	s_nop 0
	global_load_lds_dwordx4 v[10:11], off
	s_mov_b32 m0, s11
	v_or_b32_e32 v10, s55, v95
	v_mad_u64_u32 v[4:5], s[10:11], v10, s83, v[4:5]
	v_mad_i32_i24 v5, s59, v240, v5
	v_lshl_add_u64 v[10:11], v[4:5], 0, s[76:77]
	v_lshl_add_u64 v[10:11], v[10:11], 0, v[0:1]
	s_add_i32 s10, s73, 0xc00
	s_mov_b32 s11, m0
	s_mov_b32 m0, s10
	s_nop 0
	global_load_lds_dwordx4 v[10:11], off
	s_mov_b32 m0, s11
	v_lshlrev_b32_e32 v0, 4, v36
	v_lshl_add_u64 v[8:9], v[8:9], 0, v[0:1]
	s_add_i32 s10, s73, 0x1000
	s_mov_b32 s11, m0
	s_mov_b32 m0, s10
	s_nop 0
	global_load_lds_dwordx4 v[8:9], off
	s_mov_b32 m0, s11
	v_lshl_add_u64 v[6:7], v[6:7], 0, s[74:75]
	v_lshl_add_u64 v[2:3], v[2:3], 0, s[74:75]
	v_lshl_add_u64 v[6:7], v[6:7], 0, v[0:1]
	s_add_i32 s10, s73, 0x1400
	s_mov_b32 s11, m0
	s_mov_b32 m0, s10
	s_nop 0
	global_load_lds_dwordx4 v[6:7], off
	s_mov_b32 m0, s11
	v_lshl_add_u64 v[2:3], v[2:3], 0, v[0:1]
	s_add_i32 s10, s73, 0x1800
	s_mov_b32 s11, m0
	s_mov_b32 m0, s10
	s_nop 0
	global_load_lds_dwordx4 v[2:3], off
	s_mov_b32 m0, s11
	v_lshl_add_u64 v[2:3], v[4:5], 0, s[74:75]
	v_lshl_add_u64 v[2:3], v[2:3], 0, v[0:1]
	s_add_i32 s10, s73, 0x1c00
	s_mov_b32 s11, m0
	s_mov_b32 m0, s10
	s_nop 0
	global_load_lds_dwordx4 v[2:3], off
	s_mov_b32 m0, s11
	s_mov_b64 s[10:11], -1
	s_cmp_gt_i32 s12, -1
	s_cbranch_scc1 .LBB0_457
	v_lshlrev_b32_e32 v0, 2, v35
	s_mov_b64 s[10:11], 0

.LBB0_697:
	s_waitcnt vmcnt(0)
.LBB0_698:
	s_mov_b64 s[8:9], s[0:1]
	s_load_dwordx2 s[12:13], s[8:9], 0x90
	v_mov_b32_e32 v0, v232
	s_mov_b64 s[14:15], s[2:3]
	s_waitcnt lgkmcnt(0)
	s_add_u32 s8, s12, 0x6200000
	s_addc_u32 s9, s13, 0
	s_add_u32 s22, s12, 0xe200000
	s_addc_u32 s23, s13, 0
	s_add_u32 s10, s12, 0xef00000
	s_addc_u32 s11, s13, 0
	s_add_u32 s12, s12, 0x8200000
	s_addc_u32 s13, s13, 0
	s_barrier
	s_branch .LBB0_700
